# norm rewrite + SSD S2 hand schedule + SSD item XCD remap
# speedup vs baseline: 1.0174x; 1.0142x over previous
; __device__ __forceinline__ void norm_mod_rows(const float* __restrict__ xp, const float* __restrict__ xs, const float* __restrict__ gvec, const float* __restrict__ mod, int ch_shift, int ch_scale, ...
;     for (int r0 = gw; r0 < nrows; r0 += 2 * NGW) {
;         const int r1 = r0 + NGW; const bool two = r1 < nrows;
;         const int gr0 = row_base + r0, gr1 = row_base + (two ? r1 : r0);
;         const float* xrow0 = gr0 < MP ? xp + (size_t)gr0 * DM : xs + (size_t)(gr0 - MP) * DM;
;         const float* xrow1 = gr1 < MP ? xp + (size_t)gr1 * DM : xs + (size_t)(gr1 - MP) * DM;
;         f32x4 v0[4], v1[4]; float s0 = 0.f, s1 = 0.f;
; #pragma unroll
;         for (int j = 0; j < 4; ++j) { v0[j] = ((const f32x4*)xrow0)[lane + 64 * j]; v1[j] = ((const f32x4*)xrow1)[lane + 64 * j]; }
; #pragma unroll
;         for (int j = 0; j < 4; ++j) { s0 += (v0[j][0] * v0[j][0] + v0[j][1] * v0[j][1]) + (v0[j][2] * v0[j][2] + v0[j][3] * v0[j][3]);
;                                       s1 += (v1[j][0] * v1[j][0] + v1[j][1] * v1[j][1]) + (v1[j][2] * v1[j][2] + v1[j][3] * v1[j][3]); }
;         const float rstd0 = rsqrtf(wave_sum(s0) * (1.f / DM) + EPS), rstd1 = rsqrtf(wave_sum(s1) * (1.f / DM) + EPS);
; #pragma unroll
;         for (int q = 0; q < 2; ++q) {
;             if (q == 1 && !two) break;
;             const int gr = q ? gr1 : gr0, r = q ? r1 : r0; const float rstd = q ? rstd1 : rstd0;
;             const int seq = gr < MP ? (gr >> 11) : NPB + ((gr - MP) >> 6);
;             const float* mrow = mod + (size_t)seq * (6 * DM);
;             u32x2* o8 = (u32x2*)(H + (size_t)r * DM);
;             f32x4 gq[4], scq[4], shq[4];
; #pragma unroll
;             for (int j = 0; j < 4; ++j) { const int ci = lane + 64 * j;
;                 gq[j] = ((const f32x4*)gvec)[ci]; scq[j] = ((const f32x4*)(mrow + ch_scale * DM))[ci]; shq[j] = ((const f32x4*)(mrow + ch_shift * DM))[ci]; }
.Lnorm_loop_p1:
	s_lshl_b32 s9, s3, 1
	s_add_i32 s10, s9, s8
	s_lshl_b32 s22, s9, 11
	s_add_u32 s20, s12, s22
	s_addc_u32 s21, s13, 0
	s_add_i32 s9, s10, 0xffff8000
	s_ashr_i32 s22, s10, 11
	s_lshr_b32 s16, s9, 6
	s_add_i32 s16, s16, 16
	s_cmp_lt_i32 s10, 0x8000
	s_cselect_b32 s14, s30, s34
	s_cselect_b32 s15, s31, s35
	s_cselect_b32 s9, s10, s9
	s_cselect_b32 s22, s22, s16
	s_lshl_b32 s9, s9, 12
	s_add_u32 s14, s14, s9
	s_addc_u32 s15, s15, 0
	s_mul_i32 s22, s22, 0x6000
	v_readlane_b32 s16, v255, 24
	v_readlane_b32 s17, v255, 26
	s_add_u32 s16, s16, s22
	s_addc_u32 s17, s17, 0
	global_load_dwordx4 v[18:21], v85, s[14:15]
	global_load_dwordx4 v[22:25], v85, s[14:15] offset:1024
	global_load_dwordx4 v[26:29], v85, s[14:15] offset:2048
	global_load_dwordx4 v[30:33], v85, s[14:15] offset:3072
	global_load_dwordx4 v[34:37], v86, s[14:15]
	global_load_dwordx4 v[38:41], v86, s[14:15] offset:1024
	global_load_dwordx4 v[42:45], v86, s[14:15] offset:2048
	global_load_dwordx4 v[46:49], v86, s[14:15] offset:3072
	global_load_dwordx4 v[50:53], v88, s[16:17]
	global_load_dwordx4 v[54:57], v88, s[16:17] offset:1024
	global_load_dwordx4 v[58:61], v88, s[16:17] offset:2048
	global_load_dwordx4 v[62:65], v88, s[16:17] offset:3072
	global_load_dwordx4 v[66:69], v87, s[16:17]
	global_load_dwordx4 v[70:73], v87, s[16:17] offset:1024
	global_load_dwordx4 v[74:77], v87, s[16:17] offset:2048
	global_load_dwordx4 v[78:81], v87, s[16:17] offset:3072
	s_waitcnt vmcnt(15)
	v_pk_mul_f32 v[82:83], v[18:19], v[18:19]
	v_pk_fma_f32 v[82:83], v[20:21], v[20:21], v[82:83]
	s_waitcnt vmcnt(14)
	v_pk_fma_f32 v[82:83], v[22:23], v[22:23], v[82:83]
	v_pk_fma_f32 v[82:83], v[24:25], v[24:25], v[82:83]
	s_waitcnt vmcnt(13)
	v_pk_fma_f32 v[82:83], v[26:27], v[26:27], v[82:83]
	v_pk_fma_f32 v[82:83], v[28:29], v[28:29], v[82:83]
	s_waitcnt vmcnt(12)
	v_pk_fma_f32 v[82:83], v[30:31], v[30:31], v[82:83]
	v_pk_fma_f32 v[82:83], v[32:33], v[32:33], v[82:83]
	s_waitcnt vmcnt(11)
	v_pk_mul_f32 v[90:91], v[34:35], v[34:35]
	v_pk_fma_f32 v[90:91], v[36:37], v[36:37], v[90:91]
	s_waitcnt vmcnt(10)
	v_pk_fma_f32 v[90:91], v[38:39], v[38:39], v[90:91]
	v_pk_fma_f32 v[90:91], v[40:41], v[40:41], v[90:91]
	s_waitcnt vmcnt(9)
	v_pk_fma_f32 v[90:91], v[42:43], v[42:43], v[90:91]
	v_pk_fma_f32 v[90:91], v[44:45], v[44:45], v[90:91]
	s_waitcnt vmcnt(8)
	v_pk_fma_f32 v[90:91], v[46:47], v[46:47], v[90:91]
	v_pk_fma_f32 v[90:91], v[48:49], v[48:49], v[90:91]
	s_nop 0
	v_add_f32_e32 v82, v82, v83
	v_add_f32_e32 v90, v90, v91
	s_nop 1
	v_add_f32_dpp v82, v82, v82 quad_perm:[1,0,3,2] row_mask:0xf bank_mask:0xf bound_ctrl:1
	v_add_f32_dpp v90, v90, v90 quad_perm:[1,0,3,2] row_mask:0xf bank_mask:0xf bound_ctrl:1
	s_nop 1
	v_add_f32_dpp v82, v82, v82 quad_perm:[2,3,0,1] row_mask:0xf bank_mask:0xf bound_ctrl:1
	v_add_f32_dpp v90, v90, v90 quad_perm:[2,3,0,1] row_mask:0xf bank_mask:0xf bound_ctrl:1
	s_nop 1
	v_add_f32_dpp v82, v82, v82 row_half_mirror row_mask:0xf bank_mask:0xf bound_ctrl:1
	v_add_f32_dpp v90, v90, v90 row_half_mirror row_mask:0xf bank_mask:0xf bound_ctrl:1
	s_nop 1
	v_add_f32_dpp v82, v82, v82 row_mirror row_mask:0xf bank_mask:0xf bound_ctrl:1
	v_add_f32_dpp v90, v90, v90 row_mirror row_mask:0xf bank_mask:0xf bound_ctrl:1
	s_nop 1
	v_add_f32_dpp v82, v82, v82 row_bcast:15 row_mask:0xa bank_mask:0xf
	v_add_f32_dpp v90, v90, v90 row_bcast:15 row_mask:0xa bank_mask:0xf
	s_nop 1
	v_add_f32_dpp v82, v82, v82 row_bcast:31 row_mask:0xc bank_mask:0xf
	v_add_f32_dpp v90, v90, v90 row_bcast:31 row_mask:0xc bank_mask:0xf
	s_nop 1
	v_readlane_b32 s9, v82, 63
	v_readlane_b32 s10, v90, 63
	s_nop 2
	v_mov_b32_e32 v92, s9
	v_mov_b32_e32 v94, s10
	v_fmamk_f32 v92, v92, 0x3a800000, v167
	v_fmamk_f32 v94, v94, 0x3a800000, v167
	v_rsq_f32_e32 v92, v92
	v_rsq_f32_e32 v94, v94
	s_waitcnt vmcnt(4)
; __device__ __forceinline__ unsigned pk2(float lo, float hi) { unsigned r; asm("v_cvt_pk_bf16_f32 %0, %1, %2" : "=v"(r) : "v"(lo), "v"(hi)); return r; }
; __device__ __forceinline__ void norm_mod_rows(const float* __restrict__ xp, const float* __restrict__ xs, const float* __restrict__ gvec, const float* __restrict__ mod, int ch_shift, int ch_scale, ...
;     ...
; #pragma unroll
;             for (int j = 0; j < 4; ++j) { const int ci = lane + 64 * j;
;                 const f32x4 y = ((q ? v1[j] : v0[j]) * rstd) * gq[j] * (scq[j] + 1.f) + shq[j];
;                 u32x2 w; w.x = pk2(y[0], y[1]); w.y = pk2(y[2], y[3]); o8[ci] = w; }
;         }
	v_pk_add_f32 v[50:51], v[50:51], 1.0 op_sel_hi:[1,0]
	v_pk_add_f32 v[52:53], v[52:53], 1.0 op_sel_hi:[1,0]
	v_pk_add_f32 v[54:55], v[54:55], 1.0 op_sel_hi:[1,0]
	v_pk_add_f32 v[56:57], v[56:57], 1.0 op_sel_hi:[1,0]
	v_pk_add_f32 v[58:59], v[58:59], 1.0 op_sel_hi:[1,0]
	v_pk_add_f32 v[60:61], v[60:61], 1.0 op_sel_hi:[1,0]
	v_pk_add_f32 v[62:63], v[62:63], 1.0 op_sel_hi:[1,0]
	v_pk_add_f32 v[64:65], v[64:65], 1.0 op_sel_hi:[1,0]
	s_waitcnt vmcnt(0)
	v_pk_mul_f32 v[18:19], v[18:19], v[92:93] op_sel_hi:[1,0]
	v_pk_mul_f32 v[20:21], v[20:21], v[92:93] op_sel_hi:[1,0]
	v_pk_mul_f32 v[22:23], v[22:23], v[92:93] op_sel_hi:[1,0]
	v_pk_mul_f32 v[24:25], v[24:25], v[92:93] op_sel_hi:[1,0]
	v_pk_mul_f32 v[26:27], v[26:27], v[92:93] op_sel_hi:[1,0]
	v_pk_mul_f32 v[28:29], v[28:29], v[92:93] op_sel_hi:[1,0]
	v_pk_mul_f32 v[30:31], v[30:31], v[92:93] op_sel_hi:[1,0]
	v_pk_mul_f32 v[32:33], v[32:33], v[92:93] op_sel_hi:[1,0]
	v_pk_mul_f32 v[18:19], v[2:3], v[18:19]
	v_pk_mul_f32 v[20:21], v[4:5], v[20:21]
	v_pk_mul_f32 v[22:23], v[6:7], v[22:23]
	v_pk_mul_f32 v[24:25], v[8:9], v[24:25]
	v_pk_mul_f32 v[26:27], v[10:11], v[26:27]
	v_pk_mul_f32 v[28:29], v[12:13], v[28:29]
	v_pk_mul_f32 v[30:31], v[14:15], v[30:31]
	v_pk_mul_f32 v[32:33], v[16:17], v[32:33]
	v_pk_fma_f32 v[18:19], v[50:51], v[18:19], v[66:67]
	v_pk_fma_f32 v[20:21], v[52:53], v[20:21], v[68:69]
	v_pk_fma_f32 v[22:23], v[54:55], v[22:23], v[70:71]
	v_pk_fma_f32 v[24:25], v[56:57], v[24:25], v[72:73]
	v_pk_fma_f32 v[26:27], v[58:59], v[26:27], v[74:75]
	v_pk_fma_f32 v[28:29], v[60:61], v[28:29], v[76:77]
	v_pk_fma_f32 v[30:31], v[62:63], v[30:31], v[78:79]
	v_pk_fma_f32 v[32:33], v[64:65], v[32:33], v[80:81]
	v_cvt_pk_bf16_f32 v18, v18, v19
	v_cvt_pk_bf16_f32 v19, v20, v21
	v_cvt_pk_bf16_f32 v22, v22, v23
	v_cvt_pk_bf16_f32 v23, v24, v25
	v_cvt_pk_bf16_f32 v26, v26, v27
	v_cvt_pk_bf16_f32 v27, v28, v29
	v_cvt_pk_bf16_f32 v30, v30, v31
	v_cvt_pk_bf16_f32 v31, v32, v33
	global_store_dwordx2 v0, v[18:19], s[20:21]
	global_store_dwordx2 v0, v[22:23], s[20:21] offset:512
	global_store_dwordx2 v0, v[26:27], s[20:21] offset:1024
	global_store_dwordx2 v0, v[30:31], s[20:21] offset:1536
	v_pk_mul_f32 v[34:35], v[34:35], v[94:95] op_sel_hi:[1,0]
	v_pk_mul_f32 v[36:37], v[36:37], v[94:95] op_sel_hi:[1,0]
	v_pk_mul_f32 v[38:39], v[38:39], v[94:95] op_sel_hi:[1,0]
	v_pk_mul_f32 v[40:41], v[40:41], v[94:95] op_sel_hi:[1,0]
	v_pk_mul_f32 v[42:43], v[42:43], v[94:95] op_sel_hi:[1,0]
	v_pk_mul_f32 v[44:45], v[44:45], v[94:95] op_sel_hi:[1,0]
	v_pk_mul_f32 v[46:47], v[46:47], v[94:95] op_sel_hi:[1,0]
	v_pk_mul_f32 v[48:49], v[48:49], v[94:95] op_sel_hi:[1,0]
	v_pk_mul_f32 v[34:35], v[2:3], v[34:35]
	v_pk_mul_f32 v[36:37], v[4:5], v[36:37]
	v_pk_mul_f32 v[38:39], v[6:7], v[38:39]
	v_pk_mul_f32 v[40:41], v[8:9], v[40:41]
	v_pk_mul_f32 v[42:43], v[10:11], v[42:43]
	v_pk_mul_f32 v[44:45], v[12:13], v[44:45]
	v_pk_mul_f32 v[46:47], v[14:15], v[46:47]
	v_pk_mul_f32 v[48:49], v[16:17], v[48:49]
	v_pk_fma_f32 v[34:35], v[50:51], v[34:35], v[66:67]
	v_pk_fma_f32 v[36:37], v[52:53], v[36:37], v[68:69]
	v_pk_fma_f32 v[38:39], v[54:55], v[38:39], v[70:71]
	v_pk_fma_f32 v[40:41], v[56:57], v[40:41], v[72:73]
	v_pk_fma_f32 v[42:43], v[58:59], v[42:43], v[74:75]
	v_pk_fma_f32 v[44:45], v[60:61], v[44:45], v[76:77]
	v_pk_fma_f32 v[46:47], v[62:63], v[46:47], v[78:79]
	v_pk_fma_f32 v[48:49], v[64:65], v[48:49], v[80:81]
	v_cvt_pk_bf16_f32 v34, v34, v35
	v_cvt_pk_bf16_f32 v35, v36, v37
	v_cvt_pk_bf16_f32 v38, v38, v39
	v_cvt_pk_bf16_f32 v39, v40, v41
	v_cvt_pk_bf16_f32 v42, v42, v43
	v_cvt_pk_bf16_f32 v43, v44, v45
	v_cvt_pk_bf16_f32 v46, v46, v47
	v_cvt_pk_bf16_f32 v47, v48, v49
	global_store_dwordx2 v0, v[34:35], s[20:21] offset:2048
	global_store_dwordx2 v0, v[38:39], s[20:21] offset:2560
	global_store_dwordx2 v0, v[42:43], s[20:21] offset:3072
	global_store_dwordx2 v0, v[46:47], s[20:21] offset:3584
	s_add_i32 s3, s3, s5
	s_cmp_lt_i32 s3, s4
	s_cbranch_scc1 .Lnorm_loop_p1

; __device__ __forceinline__ void ssd_item(const Args& a, LAS unsigned char* lds, int layer, bool is_sample, int b, int h, int seq_row0, int nchunks,
;                                          bf16_t* proj, float* ssq, const int tid) {
;     const int wave = __builtin_amdgcn_readfirstlane(tid >> 6), lane = tid & 63, fr = lane & 15, fq = lane >> 4;
;     const int grp = h >> 3, tok = tid >> 3, oct = tid & 7;
;     float cw[4][8], cb[8];
;     {
;         const int chx = h * 64 + wave * 8;
;         const float* wp = a.in[14] + (size_t)layer * 4 * CONVC + chx; const float* bp = a.in[15] + (size_t)layer * CONVC + chx;
; #pragma unroll
;         for (int k = 0; k < 4; ++k) { const f32x4 w0 = *(const f32x4*)(wp + k * CONVC), w1 = *(const f32x4*)(wp + k * CONVC + 4);
;             cw[k][0] = w0[0]; cw[k][1] = w0[1]; cw[k][2] = w0[2]; cw[k][3] = w0[3]; cw[k][4] = w1[0]; cw[k][5] = w1[1]; cw[k][6] = w1[2]; cw[k][7] = w1[3]; }
;         const f32x4 b0 = *(const f32x4*)bp, b1 = *(const f32x4*)(bp + 4);
;         cb[0] = b0[0]; cb[1] = b0[1]; cb[2] = b0[2]; cb[3] = b0[3]; cb[4] = b1[0]; cb[5] = b1[1]; cb[6] = b1[2]; cb[7] = b1[3];
;     }
;     const float dtb = a.in[16][layer * NH + h], Aneg = -__expf(a.in[17][layer * NH + h]), dsk = a.in[18][layer * NH + h];
;     const int pb = wave >> 1, nb0 = (wave & 1) * 4, rb = wave >> 1;
;     f32x4 st[4];
;     float* ssm_out = a.out + (is_sample ? O_SSMS + ((size_t)(layer * NSB + b) * NH + h) * 8192 : O_SSMP + ((size_t)(layer * NPB + b) * NH + h) * 8192);
;     if (is_sample) {
;         const float* sp = a.in[5] + ((size_t)(layer * NSB + b) * NH + h) * 8192;
; #pragma unroll
;         for (int i = 0; i < 4; ++i)
;             st[i] = __builtin_nontemporal_load((const f32x4*)(sp + (16 * pb + fr) * DSTATE + 16 * (nb0 + i) + 4 * fq));
;     } else {
; #pragma unroll
;         for (int i = 0; i < 4; ++i) st[i] = (f32x4){0.f, 0.f, 0.f, 0.f};
;     }
;     LAS float* dt_all = (LAS float*)(lds + L_DT); LAS float* ac_all = (LAS float*)(lds + L_AC);
; __global__ void __launch_bounds__(512, 2) mega_fwd(Args a) {
;     ...
;                 for (int L = bx; L < total; L += G) {
;                     int r = L;
;                     if (r < nP) { const int b = slab * 8 + r / NH, h = r % NH; OPAQUE_TID(); ssd_item(a, lds, layer, false, b, h, b * SEQ - row_base, 32, proj, ssq, tq); continue; } r -= nP;
.LBB0_534:
	s_andn2_b64 vcc, exec, s[4:5]
	s_cbranch_vccnz .LBB0_427
	s_and_b32 s4, s3, 7
	s_lshl_b32 s4, s4, 2
	s_lshr_b32 s10, s3, 6
	s_add_i32 s4, s4, s10
	s_lshl_b32 s4, s4, 3
	s_bfe_u32 s10, s3, 0x30003
	s_add_i32 s4, s4, s10
	s_ashr_i32 s10, s4, 5
	s_and_b32 s8, s4, 31
	v_readlane_b32 s5, v255, 38
	v_mov_b32_e32 v94, v166
	s_add_i32 s10, s10, s5
	v_readfirstlane_b32 s15, v94
	s_lshl_b32 s4, s10, 11
	v_readlane_b32 s5, v255, 31
	s_ashr_i32 s23, s15, 6
	s_sub_i32 s14, s4, s5
	s_lshl_b32 s20, s8, 6
	s_lshl_b32 s4, s23, 3
	s_add_i32 s4, s4, s20
	s_ashr_i32 s5, s4, 31
	s_lshl_b64 s[4:5], s[4:5], 2
	v_readlane_b32 s6, v255, 9
	v_readlane_b32 s7, v255, 10
	s_add_u32 s6, s6, s4
	s_addc_u32 s7, s7, s5
	s_add_u32 s16, s6, 0x3000
	s_addc_u32 s17, s7, 0
	s_nop 0
	global_load_dwordx4 v[2:5], v1, s[6:7] offset:16
	global_load_dwordx4 v[6:9], v1, s[6:7]
	global_load_dwordx4 v[10:13], v197, s[6:7]
	global_load_dwordx4 v[14:17], v1, s[16:17] offset:16
	s_add_u32 s16, s6, 0x6000
	s_addc_u32 s17, s7, 0
	global_load_dwordx4 v[18:21], v198, s[6:7]
	global_load_dwordx4 v[22:25], v1, s[16:17] offset:16
	s_add_u32 s16, s6, 0x9000
	s_addc_u32 s17, s7, 0
	global_load_dwordx4 v[26:29], v199, s[6:7]
	global_load_dwordx4 v[30:33], v1, s[16:17] offset:16
	v_readlane_b32 s6, v255, 11
	v_readlane_b32 s7, v255, 12
	s_add_u32 s4, s6, s4
	s_addc_u32 s5, s7, s5
	global_load_dwordx4 v[34:37], v1, s[4:5] offset:16
	global_load_dwordx4 v[38:41], v1, s[4:5]
	v_readlane_b32 s4, v255, 13
	s_add_i32 s4, s8, s4
	s_ashr_i32 s5, s4, 31
	s_lshl_b64 s[4:5], s[4:5], 2
	s_add_u32 s6, s76, s4
	s_addc_u32 s7, s77, s5
	global_load_dword v71, v1, s[6:7]
	s_add_u32 s6, s78, s4
	s_addc_u32 s7, s79, s5
	s_add_u32 s4, s80, s4
	v_ashrrev_i32_e32 v66, 3, v94
	v_and_b32_e32 v69, 7, v94
	s_addc_u32 s5, s81, s5
	global_load_dword v72, v1, s[6:7]
	global_load_dword v95, v1, s[4:5]
	v_add_u32_e32 v0, s14, v66
	s_movk_i32 s5, 0x2300
	s_add_i32 s4, s20, 0x800
	v_lshlrev_b32_e32 v43, 3, v69
	v_mul_lo_u32 v42, v0, s5
	v_or_b32_e32 v0, s4, v43
	v_and_b32_e32 v70, -2, v66
	s_lshl_b32 s4, s8, 4
	v_add_lshl_u32 v96, v0, v42, 1
	v_add_u32_e32 v0, s14, v70
	s_and_b32 s4, s4, 0x7fffff80
	v_and_b32_e32 v104, 15, v94
	v_mul_lo_u32 v0, v0, s5
	s_addk_i32 s4, 0x1000
	v_add_u32_e32 v0, s4, v0
	v_lshlrev_b32_e32 v67, 4, v104
	v_lshl_or_b32 v0, v0, 1, v67
	v_lshl_add_u64 v[46:47], s[18:19], 0, v[0:1]
	v_add_u32_e32 v42, s20, v42
	s_waitcnt vmcnt(19)
	v_add_co_u32_e32 v50, vcc, 0x4000, v46
	v_or_b32_e32 v42, v42, v43
	s_nop 0
	v_addc_co_u32_e32 v51, vcc, 0, v47, vcc
	v_lshlrev_b32_e32 v98, 1, v42
	global_load_dwordx4 v[42:45], v96, s[18:19]
	global_load_dwordx4 v[58:61], v0, s[18:19]
	global_load_dwordx4 v[62:65], v[50:51], off offset:1536
	global_load_dwordx4 v[46:49], v0, s[18:19] offset:1024
	s_nop 0
	global_load_dwordx4 v[50:53], v[50:51], off offset:2560
	s_nop 0
	global_load_dwordx4 v[54:57], v98, s[18:19]
	s_ashr_i32 s9, s8, 31
	v_and_b32_e32 v68, 63, v94
	s_cmp_lt_i32 s23, 32
	v_or_b32_e32 v77, s14, v68
	v_mov_b32_e32 v75, 0
	s_cselect_b64 s[20:21], -1, 0
	s_cmp_gt_i32 s23, 31
	v_mov_b32_e32 v76, 0
	s_cbranch_scc1 .LBB0_537
	s_and_b32 s4, s15, 0xffffffc0
	v_add_u32_e32 v73, s4, v77
	v_mov_b64_e32 v[78:79], s[18:19]
	v_mad_i64_i32 v[78:79], s[4:5], v73, s33, v[78:79]
	v_lshl_add_u64 v[78:79], s[8:9], 1, v[78:79]
	v_add_co_u32_e32 v78, vcc, 0x4000, v78
	s_nop 1
	v_addc_co_u32_e32 v79, vcc, 0, v79, vcc
	global_load_ushort v73, v[78:79], off offset:1024
	s_waitcnt vmcnt(0)
	v_lshlrev_b32_e32 v76, 16, v73

; #define LAS __attribute__((address_space(3)))
; __device__ __forceinline__ bf16_t f2bf(float f) { return (bf16_t)(pk2(f, 0.f) & 0xffffu); }
; __device__ __forceinline__ float bflo(unsigned w) { return __uint_as_float(w << 16); }
; __device__ __forceinline__ float bfhi(unsigned w) { return __uint_as_float(w & 0xffff0000u); }
; __device__ __forceinline__ float siluf_(float x) { return x * __builtin_amdgcn_rcpf(1.f + __expf(-x)); }
; __device__ __forceinline__ void ssd_item(const Args& a, LAS unsigned char* lds, int layer, bool is_sample, int b, int h, int seq_row0, int nchunks,
;                                          bf16_t* proj, float* ssq, const int tid) {
;     ...
;         {
;             float o[8];
; #pragma unroll
;             for (int i = 0; i < 8; ++i) o[i] = cb[i];
; #pragma unroll
;             for (int k = 0; k < 4; ++k) { const u32x4 w = *(const LAS u32x4*)(lds + L_XRAW + (lane + k) * P64 + wave * 16);
;                 o[0] += cw[k][0] * bflo(w.x); o[1] += cw[k][1] * bfhi(w.x); o[2] += cw[k][2] * bflo(w.y); o[3] += cw[k][3] * bfhi(w.y);
;                 o[4] += cw[k][4] * bflo(w.z); o[5] += cw[k][5] * bfhi(w.z); o[6] += cw[k][6] * bflo(w.w); o[7] += cw[k][7] * bfhi(w.w); }
; #pragma unroll
;             for (int i = 0; i < 8; ++i) *(LAS bf16_t*)(lds + L_XST + (wave * 8 + i) * P64 + lane * 2) = f2bf(siluf_(o[i]));
;         }
.LBB0_570:
	ds_read_b128 v[148:151], v123
	ds_read_b128 v[152:155], v123 offset:144
	s_add_i32 s65, s15, 0
	s_add_i32 s65, s65, 0x1c73c
	v_add_u32_e32 v164, v110, v109
	s_waitcnt lgkmcnt(1)
	v_lshlrev_b32_e32 v102, 16, v148
	v_and_b32_e32 v103, 0xffff0000, v148
	v_lshlrev_b32_e32 v148, 16, v149
	v_fma_f32 v156, v8, v148, v40
	v_and_b32_e32 v148, 0xffff0000, v149
	v_fma_f32 v157, v9, v148, v41
	v_lshlrev_b32_e32 v148, 16, v150
	v_fma_f32 v158, v2, v148, v34
	v_and_b32_e32 v148, 0xffff0000, v150
	v_fma_f32 v159, v3, v148, v35
	v_lshlrev_b32_e32 v148, 16, v151
	v_fma_f32 v160, v4, v148, v36
	v_and_b32_e32 v148, 0xffff0000, v151
	v_fma_f32 v102, v6, v102, v38
	v_fma_f32 v161, v5, v148, v37
	s_waitcnt lgkmcnt(0)
	v_lshlrev_b32_e32 v148, 16, v152
	v_fma_f32 v103, v7, v103, v39
	v_fmac_f32_e32 v102, v10, v148
	v_and_b32_e32 v148, 0xffff0000, v152
	v_fmac_f32_e32 v103, v11, v148
	v_lshlrev_b32_e32 v148, 16, v153
	v_fmac_f32_e32 v156, v12, v148
	v_and_b32_e32 v148, 0xffff0000, v153
	v_fmac_f32_e32 v157, v13, v148
	v_lshlrev_b32_e32 v148, 16, v154
	v_fmac_f32_e32 v158, v14, v148
	v_and_b32_e32 v148, 0xffff0000, v154
	v_fmac_f32_e32 v159, v15, v148
	ds_read_b128 v[148:151], v123 offset:288
	v_lshlrev_b32_e32 v152, 16, v155
	v_fmac_f32_e32 v160, v16, v152
	v_and_b32_e32 v152, 0xffff0000, v155
	v_fmac_f32_e32 v161, v17, v152
	ds_read_b128 v[152:155], v123 offset:432
	s_waitcnt lgkmcnt(1)
	v_lshlrev_b32_e32 v162, 16, v148
	v_and_b32_e32 v148, 0xffff0000, v148
	v_fmac_f32_e32 v103, v19, v148
	v_lshlrev_b32_e32 v148, 16, v149
	v_fmac_f32_e32 v156, v20, v148
	v_and_b32_e32 v148, 0xffff0000, v149
	v_fmac_f32_e32 v157, v21, v148
	v_lshlrev_b32_e32 v148, 16, v150
	v_fmac_f32_e32 v158, v22, v148
	v_and_b32_e32 v148, 0xffff0000, v150
	v_fmac_f32_e32 v159, v23, v148
	v_lshlrev_b32_e32 v148, 16, v151
	v_fmac_f32_e32 v160, v24, v148
	v_and_b32_e32 v148, 0xffff0000, v151
	v_fmac_f32_e32 v102, v18, v162
	v_fmac_f32_e32 v161, v25, v148
	s_waitcnt lgkmcnt(0)
	v_lshlrev_b32_e32 v148, 16, v152
	v_fmac_f32_e32 v102, v26, v148
	v_and_b32_e32 v148, 0xffff0000, v152
	v_fmac_f32_e32 v103, v27, v148
	v_lshlrev_b32_e32 v148, 16, v153
	v_fmac_f32_e32 v156, v28, v148
	v_and_b32_e32 v148, 0xffff0000, v153
	v_fmac_f32_e32 v157, v29, v148
	v_lshlrev_b32_e32 v148, 16, v154
	v_fmac_f32_e32 v158, v30, v148
	v_and_b32_e32 v148, 0xffff0000, v154
	v_fmac_f32_e32 v159, v31, v148
	v_mul_f32_e32 v148, 0xbfb8aa3b, v102
	v_exp_f32_e32 v148, v148
	v_mul_f32_e32 v150, 0xbfb8aa3b, v103
	v_exp_f32_e32 v150, v150
	v_lshlrev_b32_e32 v149, 16, v155
	v_add_f32_e32 v148, 1.0, v148
	v_rcp_f32_e32 v148, v148
	v_fmac_f32_e32 v160, v32, v149
	v_and_b32_e32 v149, 0xffff0000, v155
	v_fmac_f32_e32 v161, v33, v149
	v_mul_f32_e32 v102, v102, v148
	v_add_f32_e32 v148, 1.0, v150
	v_mul_f32_e32 v149, 0xbfb8aa3b, v156
	v_rcp_f32_e32 v148, v148
	v_exp_f32_e32 v149, v149
	v_cvt_pk_bf16_f32 v102, v102, v1
	ds_write_b16 v124, v102
	v_mul_f32_e32 v102, v103, v148
	v_add_f32_e32 v103, 1.0, v149
	v_mul_f32_e32 v148, 0xbfb8aa3b, v157
	v_rcp_f32_e32 v103, v103
	v_exp_f32_e32 v148, v148
	v_cvt_pk_bf16_f32 v102, v102, v1
	ds_write_b16 v124, v102 offset:144
	v_mul_f32_e32 v102, v156, v103
	v_add_f32_e32 v103, 1.0, v148
	v_mul_f32_e32 v148, 0xbfb8aa3b, v158
	v_rcp_f32_e32 v103, v103
	v_exp_f32_e32 v148, v148
	v_cvt_pk_bf16_f32 v102, v102, v1
	ds_write_b16 v124, v102 offset:288
	v_mul_f32_e32 v102, v157, v103
	v_add_f32_e32 v103, 1.0, v148
	v_mul_f32_e32 v148, 0xbfb8aa3b, v159
	v_rcp_f32_e32 v103, v103
	v_exp_f32_e32 v148, v148
	v_cvt_pk_bf16_f32 v102, v102, v1
	ds_write_b16 v124, v102 offset:432
	v_mul_f32_e32 v102, v158, v103
	v_add_f32_e32 v103, 1.0, v148
	v_mul_f32_e32 v148, 0xbfb8aa3b, v160
	v_rcp_f32_e32 v103, v103
	v_exp_f32_e32 v148, v148
	v_cvt_pk_bf16_f32 v102, v102, v1
	ds_write_b16 v124, v102 offset:576
	v_mul_f32_e32 v102, v159, v103
	v_add_f32_e32 v103, 1.0, v148
	v_mul_f32_e32 v148, 0xbfb8aa3b, v161
	v_rcp_f32_e32 v103, v103
	v_exp_f32_e32 v148, v148
	v_cvt_pk_bf16_f32 v102, v102, v1
	v_add_u32_e32 v149, s15, v120
	v_add_u32_e32 v151, s15, v119
	ds_write_b16 v124, v102 offset:720
	v_mul_f32_e32 v102, v160, v103
	v_add_f32_e32 v103, 1.0, v148
	v_mov_b32_e32 v148, s65
	v_add_u32_e32 v150, 0x1a640, v149
	v_add_u32_e32 v149, 0x1c640, v149
	v_add_u32_e32 v152, 0x1a640, v151
	v_add_u32_e32 v151, 0x1c640, v151
	ds_read_b32 v148, v148
	ds_read_b32 v150, v150
	ds_read_b32 v149, v149
	ds_read_b32 v152, v152
	ds_read_b32 v151, v151
	v_rcp_f32_e32 v103, v103
	v_cvt_pk_bf16_f32 v102, v102, v1
	ds_write_b16 v124, v102 offset:864
	v_add_u32_e32 v165, s15, v117
	v_mul_f32_e32 v102, v161, v103
	s_waitcnt lgkmcnt(3)
	v_sub_f32_e32 v103, v148, v149
	s_waitcnt lgkmcnt(1)
; #define LAS __attribute__((address_space(3)))
; __device__ __forceinline__ bf16_t f2bf(float f) { return (bf16_t)(pk2(f, 0.f) & 0xffffu); }
; __device__ __forceinline__ void ssd_item(const Args& a, LAS unsigned char* lds, int layer, bool is_sample, int b, int h, int seq_row0, int nchunks,
;                                          bf16_t* proj, float* ssq, const int tid) {
;     ...
;         {
;             const int oc = tid & 15, tk = (tid >> 4) * 2;
;             const float a63s = acv[63]; const float wa = dtv[tk] * __builtin_amdgcn_exp2f(a63s - acv[tk]), wb = dtv[tk + 1] * __builtin_amdgcn_exp2f(a63s - acv[tk + 1]);
;             LAS unsigned char* d = lds + L_BWT + (oc * 8) * P64 + ((((tk >> 3) ^ ((oc >> 1) & 7)) << 4) | ((tk * 2) & 15));
;             *(LAS unsigned*)(d + 0 * P64) = pk2(bflo(bo0.x) * wa, bflo(bo1.x) * wb); *(LAS unsigned*)(d + 1 * P64) = pk2(bfhi(bo0.x) * wa, bfhi(bo1.x) * wb);
;             *(LAS unsigned*)(d + 2 * P64) = pk2(bflo(bo0.y) * wa, bflo(bo1.y) * wb); *(LAS unsigned*)(d + 3 * P64) = pk2(bfhi(bo0.y) * wa, bfhi(bo1.y) * wb);
;             *(LAS unsigned*)(d + 4 * P64) = pk2(bflo(bo0.z) * wa, bflo(bo1.z) * wb); *(LAS unsigned*)(d + 5 * P64) = pk2(bfhi(bo0.z) * wa, bfhi(bo1.z) * wb);
;             *(LAS unsigned*)(d + 6 * P64) = pk2(bflo(bo0.w) * wa, bflo(bo1.w) * wb); *(LAS unsigned*)(d + 7 * P64) = pk2(bfhi(bo0.w) * wa, bfhi(bo1.w) * wb);
;         }
;         {
;             float al[4];
; #pragma unroll
;             for (int j = 0; j < 4; ++j) al[j] = acv[16 * rb + 4 * fq + j];
; #pragma unroll
;             for (int ci = 0; ci < 2; ++ci) { const int cbk = (wave & 1) * 2 + ci; f32x4 acc = (f32x4){0.f, 0.f, 0.f, 0.f};
; #pragma unroll
;                 for (int ks = 0; ks < 4; ++ks) { const bf16x8 av = *(const LAS bf16x8*)(lds + L_CM + (16 * rb + fr) * P128 + (32 * ks + 8 * fq) * 2);
;                     const bf16x8 bv = *(const LAS bf16x8*)(lds + L_BM + (16 * cbk + fr) * P128 + (32 * ks + 8 * fq) * 2); acc = mfma16(av, bv, acc); }
;                 const int s = 16 * cbk + fr; const float as = acv[s], ds = dtv[s];
; #pragma unroll
;                 for (int j = 0; j < 4; ++j) { const int l = 16 * rb + 4 * fq + j;
;                     const float gv = (s <= l) ? acc[j] * __builtin_amdgcn_exp2f(al[j] - as) * ds : 0.f;
;                     *(LAS bf16_t*)(lds + L_G + l * P64 + s * 2) = f2bf(gv); } }
;         }
	v_sub_f32_e32 v148, v148, v151
	v_exp_f32_e32 v103, v103
	v_exp_f32_e32 v148, v148
	v_cvt_pk_bf16_f32 v102, v102, v1
	ds_write_b16 v124, v102 offset:1008
	v_mul_f32_e32 v102, v150, v103
	v_mul_f32_e32 v103, v152, v148
	v_lshlrev_b32_e32 v148, 16, v58
	v_lshlrev_b32_e32 v149, 16, v62
	v_and_b32_e32 v58, 0xffff0000, v58
	v_and_b32_e32 v62, 0xffff0000, v62
	v_mul_f32_e32 v58, v102, v58
	v_mul_f32_e32 v62, v103, v62
	v_mul_f32_e32 v148, v102, v148
	v_cvt_pk_bf16_f32 v58, v58, v62
	v_add_u32_e32 v62, 0xd000, v125
	v_mul_f32_e32 v149, v103, v149
	v_cvt_pk_bf16_f32 v148, v148, v149
	ds_write2_b32 v62, v148, v58 offset1:36
	v_lshlrev_b32_e32 v58, 16, v59
	v_and_b32_e32 v59, 0xffff0000, v59
	v_mul_f32_e32 v58, v102, v58
	v_lshlrev_b32_e32 v148, 16, v63
	v_mul_f32_e32 v59, v102, v59
	v_and_b32_e32 v63, 0xffff0000, v63
	v_mul_f32_e32 v148, v103, v148
	v_cvt_pk_bf16_f32 v58, v58, v148
	v_mul_f32_e32 v63, v103, v63
	v_cvt_pk_bf16_f32 v59, v59, v63
	ds_write2_b32 v62, v58, v59 offset0:72 offset1:108
	v_lshlrev_b32_e32 v58, 16, v60
	v_lshlrev_b32_e32 v59, 16, v64
	v_mul_f32_e32 v58, v102, v58
	v_mul_f32_e32 v59, v103, v59
	v_cvt_pk_bf16_f32 v58, v58, v59
	v_and_b32_e32 v59, 0xffff0000, v60
	v_mul_f32_e32 v59, v102, v59
	v_and_b32_e32 v60, 0xffff0000, v64
	v_mul_f32_e32 v60, v103, v60
	v_cvt_pk_bf16_f32 v59, v59, v60
	ds_write2_b32 v62, v58, v59 offset0:144 offset1:180
	v_lshlrev_b32_e32 v58, 16, v61
	v_lshlrev_b32_e32 v59, 16, v65
	v_mul_f32_e32 v58, v102, v58
	v_mul_f32_e32 v59, v103, v59
	v_cvt_pk_bf16_f32 v58, v58, v59
	v_and_b32_e32 v59, 0xffff0000, v61
	v_mul_f32_e32 v59, v102, v59
	v_and_b32_e32 v60, 0xffff0000, v65
	v_mul_f32_e32 v60, v103, v60
	v_cvt_pk_bf16_f32 v59, v59, v60
	ds_write2_b32 v62, v58, v59 offset0:216 offset1:252
	ds_read_b128 v[58:61], v164 offset:18432
	v_add_u32_e32 v102, v111, v109
	ds_read_b128 v[62:65], v102 offset:35840
	ds_read_b128 v[148:151], v164 offset:18496
	ds_read_b128 v[152:155], v164 offset:18624
	s_waitcnt lgkmcnt(2)
	v_mfma_f32_16x16x32_bf16 v[58:61], v[58:61], v[62:65], 0
	ds_read_b128 v[62:65], v164 offset:18560
	ds_read_b128 v[156:159], v102 offset:35904
	ds_read_b128 v[160:163], v102 offset:35968
	v_add_u32_e32 v103, s15, v118
	v_add_u32_e32 v103, 0x1c640, v103
	s_waitcnt lgkmcnt(1)
	v_mfma_f32_16x16x32_bf16 v[58:61], v[148:151], v[156:159], v[58:61]
	ds_read_b128 v[148:151], v103
	v_add_u32_e32 v157, 0x1a640, v165
	v_add_u32_e32 v158, 0x1c680, v165
	s_waitcnt lgkmcnt(1)
	v_mfma_f32_16x16x32_bf16 v[58:61], v[62:65], v[160:163], v[58:61]
	v_add_u32_e32 v62, 0x1c640, v165
	ds_read_b32 v156, v62
	ds_read_b128 v[62:65], v102 offset:36032
	ds_read_b32 v102, v157
	ds_read_b32 v169, v158
	s_waitcnt lgkmcnt(2)
	v_mfma_f32_16x16x32_bf16 v[58:61], v[152:155], v[62:65], v[58:61]
	v_sub_f32_e32 v157, v148, v156
	v_exp_f32_e32 v157, v157
	v_sub_f32_e32 v62, v149, v156
	v_exp_f32_e32 v62, v62
	v_add_u32_e32 v63, v112, v113
	s_nop 2
	v_mul_f32_e32 v58, v58, v157
	s_waitcnt lgkmcnt(1)
	v_mul_f32_e32 v58, v102, v58
	v_cndmask_b32_e64 v58, v58, 0, s[40:41]
	v_cvt_pk_bf16_f32 v58, v58, v1
	ds_write_b16 v63, v58 offset:9216
	v_mul_f32_e32 v58, v59, v62
	v_sub_f32_e32 v59, v150, v156
	v_exp_f32_e32 v59, v59
	v_mul_f32_e32 v58, v102, v58
	v_cndmask_b32_e64 v58, v58, 0, s[42:43]
	v_cvt_pk_bf16_f32 v58, v58, v1
	ds_write_b16 v63, v58 offset:9360
	v_mul_f32_e32 v58, v60, v59
	v_sub_f32_e32 v59, v151, v156
	v_exp_f32_e32 v59, v59
	v_mul_f32_e32 v58, v102, v58
	v_cndmask_b32_e64 v58, v58, 0, s[44:45]
	v_cvt_pk_bf16_f32 v58, v58, v1
	ds_write_b16 v63, v58 offset:9504
	v_mul_f32_e32 v58, v61, v59
	v_mul_f32_e32 v58, v102, v58
	v_cndmask_b32_e64 v58, v58, 0, s[46:47]
	v_cvt_pk_bf16_f32 v58, v58, v1
	ds_write_b16 v63, v58 offset:9648
	ds_read_b128 v[58:61], v164 offset:18432
	v_add_u32_e32 v102, v114, v109
	ds_read_b128 v[62:65], v164 offset:18496
	ds_read_b128 v[152:155], v102 offset:35840
	ds_read_b128 v[156:159], v102 offset:35904
	s_waitcnt lgkmcnt(1)
	v_mfma_f32_16x16x32_bf16 v[58:61], v[58:61], v[152:155], 0
	ds_read_b128 v[152:155], v164 offset:18560
	s_waitcnt lgkmcnt(1)
	v_mfma_f32_16x16x32_bf16 v[58:61], v[62:65], v[156:159], v[58:61]
	ds_read_b128 v[62:65], v102 offset:35968
	ds_read_b128 v[156:159], v164 offset:18624
	ds_read_b128 v[160:163], v102 offset:36032
	s_waitcnt lgkmcnt(2)
	v_mfma_f32_16x16x32_bf16 v[58:61], v[152:155], v[62:65], v[58:61]
	v_sub_f32_e32 v63, v148, v169
	v_add_u32_e32 v62, 0x1a680, v165
	v_exp_f32_e32 v63, v63
	s_waitcnt lgkmcnt(0)
	v_mfma_f32_16x16x32_bf16 v[58:61], v[156:159], v[160:163], v[58:61]
	ds_read_b32 v62, v62
	v_add_u32_e32 v64, v115, v113
	s_nop 5
	v_mul_f32_e32 v58, v58, v63
	v_sub_f32_e32 v63, v149, v169
	v_exp_f32_e32 v63, v63
	s_waitcnt lgkmcnt(0)
	v_mul_f32_e32 v58, v62, v58
	v_cndmask_b32_e64 v58, v58, 0, s[48:49]
	v_cvt_pk_bf16_f32 v58, v58, v1
	ds_write_b16 v64, v58 offset:9216
	v_mul_f32_e32 v58, v59, v63
	v_sub_f32_e32 v59, v150, v169
	v_exp_f32_e32 v59, v59
	v_mul_f32_e32 v58, v62, v58
	v_cndmask_b32_e64 v58, v58, 0, s[50:51]
	v_cvt_pk_bf16_f32 v58, v58, v1
	ds_write_b16 v64, v58 offset:9360
	v_mul_f32_e32 v58, v60, v59
	v_sub_f32_e32 v59, v151, v169
	v_exp_f32_e32 v59, v59
	v_mul_f32_e32 v58, v62, v58
	v_cndmask_b32_e64 v58, v58, 0, s[52:53]
	v_cvt_pk_bf16_f32 v58, v58, v1
	ds_write_b16 v64, v58 offset:9504
	v_mul_f32_e32 v58, v61, v59
	v_mul_f32_e32 v58, v62, v58
	v_cndmask_b32_e64 v58, v58, 0, s[54:55]
	v_cvt_pk_bf16_f32 v58, v58, v1
	ds_write_b16 v64, v58 offset:9648
	s_waitcnt lgkmcnt(0)
	s_barrier
; __device__ __forceinline__ void ssd_item(const Args& a, LAS unsigned char* lds, int layer, bool is_sample, int b, int h, int seq_row0, int nchunks,
;                                          bf16_t* proj, float* ssq, const int tid) {
;     ...
;         {
;             float sq[4] = {0.f, 0.f, 0.f, 0.f}, el[4];
; #pragma unroll
;             for (int j = 0; j < 4; ++j) el[j] = __builtin_amdgcn_exp2f(acv[16 * rb + 4 * fq + j]);
; #pragma unroll
;             for (int ci = 0; ci < 2; ++ci) { const int cbk = (wave & 1) * 2 + ci; f32x4 acc = (f32x4){0.f, 0.f, 0.f, 0.f}, acp = (f32x4){0.f, 0.f, 0.f, 0.f};
; #pragma unroll
;                 for (int ks = 0; ks < 2; ++ks) { const bf16x8 av = *(const LAS bf16x8*)(lds + L_G + (16 * rb + fr) * P64 + (32 * ks + 8 * fq) * 2);
;                     const bf16x8 bv = *(const LAS bf16x8*)(lds + L_XST + (16 * cbk + fr) * P64 + (32 * ks + 8 * fq) * 2); acc = mfma16(av, bv, acc); }
; #pragma unroll
;                 for (int ks = 0; ks < 4; ++ks) { const bf16x8 av = *(const LAS bf16x8*)(lds + L_CM + (16 * rb + fr) * P128 + (32 * ks + 8 * fq) * 2);
;                     const bf16x8 bv = *(const LAS bf16x8*)(lds + L_ST + (16 * cbk + fr) * P128 + (32 * ks + 8 * fq) * 2); acp = mfma16(av, bv, acp); }
;                 const int p = 16 * cbk + fr;
;                 const u32x2 xs4 = *(const LAS u32x2*)(lds + L_XST + p * P64 + (16 * rb + 4 * fq) * 2);
;                 const float xsv[4] = {bflo(xs4.x), bfhi(xs4.x), bflo(xs4.y), bfhi(xs4.y)};
; #pragma unroll
;                 for (int j = 0; j < 4; ++j) { const int l = 16 * rb + 4 * fq + j;
;                     LAS bf16_t* zp = (LAS bf16_t*)(lds + L_ZT + l * P64 + p * 2);
;                     const float z = bf2f(*zp);
;                     const float yg = (acc[j] + el[j] * acp[j] + xsv[j] * dsk) * siluf_(z);
;                     *zp = f2bf(yg); sq[j] += yg * yg; } }
; #pragma unroll
;             for (int j = 0; j < 4; ++j) { const float v = row16_sum(sq[j]);
;                 if (fr == 0) ssqp[(16 * rb + 4 * fq + j) * 2 + (wave & 1)] = v; }
;             const float dec = __builtin_amdgcn_exp2f(acv[63]);
; #pragma unroll
;             for (int i = 0; i < 4; ++i) { st[i] = st[i] * dec;
; #pragma unroll
;                 for (int ks = 0; ks < 2; ++ks) { const bf16x8 av = *(const LAS bf16x8*)(lds + L_XST + (16 * pb + fr) * P64 + (32 * ks + 8 * fq) * 2);
	v_mov_b32_e32 v58, s65
	ds_read_b32 v102, v58
	ds_read_b128 v[148:151], v147
	ds_read_b128 v[176:179], v137 offset:53248
	ds_read_b128 v[180:183], v139 offset:53248
	ds_read_b128 v[184:187], v141 offset:53248
	ds_read_b128 v[188:191], v143 offset:53248
	ds_read_b128 v[152:155], v147 offset:64
	ds_read_b128 v[216:219], v138 offset:53248
	ds_read_b128 v[220:223], v140 offset:53248
	ds_read_b128 v[224:227], v142 offset:53248
	ds_read_b128 v[228:231], v144 offset:53248
	ds_read_b128 v[156:159], v147 offset:9216
	ds_read_b128 v[160:163], v147 offset:9280
	s_waitcnt lgkmcnt(12)
	v_exp_f32_e32 v102, v102
	s_nop 0
	v_pk_mul_f32 v[66:67], v[66:67], v[102:103] op_sel_hi:[1,0]
	v_pk_mul_f32 v[68:69], v[68:69], v[102:103] op_sel_hi:[1,0]
	v_pk_mul_f32 v[78:79], v[78:79], v[102:103] op_sel_hi:[1,0]
	v_pk_mul_f32 v[80:81], v[80:81], v[102:103] op_sel_hi:[1,0]
	v_pk_mul_f32 v[70:71], v[70:71], v[102:103] op_sel_hi:[1,0]
	v_pk_mul_f32 v[72:73], v[72:73], v[102:103] op_sel_hi:[1,0]
	v_pk_mul_f32 v[74:75], v[74:75], v[102:103] op_sel_hi:[1,0]
	v_pk_mul_f32 v[76:77], v[76:77], v[102:103] op_sel_hi:[1,0]
	s_waitcnt lgkmcnt(11)
	s_waitcnt lgkmcnt(10)
	v_mfma_f32_16x16x32_bf16 v[66:69], v[176:179], v[148:151], v[66:69]
	s_waitcnt lgkmcnt(9)
	v_mfma_f32_16x16x32_bf16 v[78:81], v[180:183], v[148:151], v[78:81]
	s_waitcnt lgkmcnt(8)
	v_mfma_f32_16x16x32_bf16 v[70:73], v[184:187], v[148:151], v[70:73]
	s_waitcnt lgkmcnt(7)
	v_mfma_f32_16x16x32_bf16 v[74:77], v[188:191], v[148:151], v[74:77]
	ds_read_b128 v[232:235], v164 offset:18432
	ds_read_b128 v[236:239], v164 offset:18496
	ds_read_b128 v[240:243], v164 offset:18560
	ds_read_b128 v[244:247], v164 offset:18624
	ds_read_b128 v[176:179], v127
	ds_read_b128 v[180:183], v127 offset:64
	ds_read_b128 v[184:187], v127 offset:128
	ds_read_b128 v[188:191], v127 offset:192
	s_waitcnt lgkmcnt(14)
	s_waitcnt lgkmcnt(13)
	v_mfma_f32_16x16x32_bf16 v[66:69], v[216:219], v[152:155], v[66:69]
	s_waitcnt lgkmcnt(12)
	v_mfma_f32_16x16x32_bf16 v[78:81], v[220:223], v[152:155], v[78:81]
	s_waitcnt lgkmcnt(11)
	v_mfma_f32_16x16x32_bf16 v[70:73], v[224:227], v[152:155], v[70:73]
	s_waitcnt lgkmcnt(10)
	v_mfma_f32_16x16x32_bf16 v[74:77], v[228:231], v[152:155], v[74:77]
	ds_read_b128 v[148:151], v126
	ds_read_b128 v[152:155], v126 offset:64
	ds_read_b128 v[192:195], v103
	ds_read_b64 v[248:249], v128
	ds_read_b64 v[250:251], v128 offset:2304
	s_waitcnt lgkmcnt(8)
	v_mfma_f32_16x16x32_bf16 v[176:179], v[232:235], v[176:179], 0
	ds_read_b128 v[216:219], v131
	ds_read_b128 v[220:223], v131 offset:64
	ds_read_b128 v[224:227], v131 offset:128
	ds_read_b128 v[228:231], v131 offset:192
	ds_read_b128 v[58:61], v130
	ds_read_b128 v[62:65], v130 offset:64
	s_waitcnt lgkmcnt(13)
	v_mfma_f32_16x16x32_bf16 v[176:179], v[236:239], v[180:183], v[176:179]
	s_waitcnt lgkmcnt(12)
	v_mfma_f32_16x16x32_bf16 v[176:179], v[240:243], v[184:187], v[176:179]
	s_waitcnt lgkmcnt(11)
	v_mfma_f32_16x16x32_bf16 v[176:179], v[244:247], v[188:191], v[176:179]
	s_waitcnt lgkmcnt(10)
	v_mfma_f32_16x16x32_bf16 v[148:151], v[156:159], v[148:151], 0
	ds_read_u16 v165, v129
	ds_read_u16 v169, v129 offset:144
	ds_read_u16 v170, v129 offset:288
	ds_read_u16 v171, v129 offset:432
	s_waitcnt lgkmcnt(13)
	v_mfma_f32_16x16x32_bf16 v[148:151], v[160:163], v[152:155], v[148:151]
	s_waitcnt lgkmcnt(9)
	v_mfma_f32_16x16x32_bf16 v[216:219], v[232:235], v[216:219], 0
	ds_read_u16 v172, v132
	ds_read_u16 v173, v132 offset:144
	ds_read_u16 v215, v132 offset:288
	ds_read_u16 v102, v132 offset:432
	s_waitcnt lgkmcnt(12)
	v_mfma_f32_16x16x32_bf16 v[216:219], v[236:239], v[220:223], v[216:219]
	s_waitcnt lgkmcnt(9)
	v_mfma_f32_16x16x32_bf16 v[58:61], v[156:159], v[58:61], 0
	s_waitcnt lgkmcnt(8)
	v_mfma_f32_16x16x32_bf16 v[58:61], v[160:163], v[62:65], v[58:61]
	v_exp_f32_e32 v192, v192
	v_exp_f32_e32 v193, v193
	v_exp_f32_e32 v194, v194
	v_exp_f32_e32 v195, v195
	v_mfma_f32_16x16x32_bf16 v[216:219], v[240:243], v[224:227], v[216:219]
	v_lshlrev_b32_e32 v180, 16, v248
	v_and_b32_e32 v181, 0xffff0000, v248
	v_lshlrev_b32_e32 v182, 16, v249
	v_and_b32_e32 v183, 0xffff0000, v249
	v_mfma_f32_16x16x32_bf16 v[216:219], v[244:247], v[228:231], v[216:219]
	s_waitcnt lgkmcnt(7)
	v_lshlrev_b32_e32 v165, 16, v165
	v_mul_f32_e32 v188, 0xbfb8aa3b, v165
	v_exp_f32_e32 v188, v188
	s_waitcnt lgkmcnt(6)
	v_lshlrev_b32_e32 v169, 16, v169
	v_mul_f32_e32 v189, 0xbfb8aa3b, v169
	v_exp_f32_e32 v189, v189
	s_waitcnt lgkmcnt(5)
	v_lshlrev_b32_e32 v170, 16, v170
	v_mul_f32_e32 v190, 0xbfb8aa3b, v170
	v_exp_f32_e32 v190, v190
	s_waitcnt lgkmcnt(4)
; #define LAS __attribute__((address_space(3)))
; __device__ __forceinline__ bf16_t f2bf(float f) { return (bf16_t)(pk2(f, 0.f) & 0xffffu); }
; __device__ __forceinline__ float bf2f(bf16_t h) { return __uint_as_float(((unsigned)h) << 16); }
; __device__ __forceinline__ float siluf_(float x) { return x * __builtin_amdgcn_rcpf(1.f + __expf(-x)); }
; __device__ __forceinline__ f32x4 mfma16(bf16x8 a, bf16x8 b, f32x4 c) { return __builtin_amdgcn_mfma_f32_16x16x32_bf16(a, b, c, 0, 0, 0); }
; #define LBAR() do { asm volatile("s_waitcnt lgkmcnt(0)" ::: "memory"); __builtin_amdgcn_s_barrier(); asm volatile("" ::: "memory"); } while (0)
; __device__ __forceinline__ void ssd_item(const Args& a, LAS unsigned char* lds, int layer, bool is_sample, int b, int h, int seq_row0, int nchunks,
;                                          bf16_t* proj, float* ssq, const int tid) {
;     ...
;                 for (int j = 0; j < 4; ++j) { const int l = 16 * rb + 4 * fq + j;
;                     LAS bf16_t* zp = (LAS bf16_t*)(lds + L_ZT + l * P64 + p * 2);
;                     const float z = bf2f(*zp);
;                     const float yg = (acc[j] + el[j] * acp[j] + xsv[j] * dsk) * siluf_(z);
;                     *zp = f2bf(yg); sq[j] += yg * yg; } }
; #pragma unroll
;             for (int j = 0; j < 4; ++j) { const float v = row16_sum(sq[j]);
;                 if (fr == 0) ssqp[(16 * rb + 4 * fq + j) * 2 + (wave & 1)] = v; }
;             const float dec = __builtin_amdgcn_exp2f(acv[63]);
; #pragma unroll
;             for (int i = 0; i < 4; ++i) { st[i] = st[i] * dec;
; #pragma unroll
;                 for (int ks = 0; ks < 2; ++ks) { const bf16x8 av = *(const LAS bf16x8*)(lds + L_XST + (16 * pb + fr) * P64 + (32 * ks + 8 * fq) * 2);
;                     const bf16x8 bv = *(const LAS bf16x8*)(lds + L_BWT + (16 * (nb0 + i) + fr) * P64 + (((4 * ks + fq) ^ ((nb0 + i) & 7)) << 4)); st[i] = mfma16(bv, av, st[i]); } }
;         }
;         LBAR();
;         if (tid < 64) ((LAS float*)(lds + L_SSQA))[c * 64 + tid] = ssqp[tid * 2] + ssqp[tid * 2 + 1];
	v_lshlrev_b32_e32 v171, 16, v171
	v_mul_f32_e32 v191, 0xbfb8aa3b, v171
	v_exp_f32_e32 v191, v191
	v_fma_f32 v148, v192, v176, v148
	v_fmac_f32_e32 v148, v95, v180
	v_fma_f32 v149, v193, v177, v149
	v_fmac_f32_e32 v149, v95, v181
	v_fma_f32 v150, v194, v178, v150
	v_fmac_f32_e32 v150, v95, v182
	v_fma_f32 v151, v195, v179, v151
	v_fmac_f32_e32 v151, v95, v183
	v_add_f32_e32 v188, 1.0, v188
	v_rcp_f32_e32 v188, v188
	v_add_f32_e32 v189, 1.0, v189
	v_rcp_f32_e32 v189, v189
	v_add_f32_e32 v190, 1.0, v190
	v_rcp_f32_e32 v190, v190
	v_add_f32_e32 v191, 1.0, v191
	v_rcp_f32_e32 v191, v191
	v_mul_f32_e32 v188, v188, v165
	v_mul_f32_e32 v152, v148, v188
	v_mul_f32_e32 v189, v189, v169
	v_mul_f32_e32 v153, v149, v189
	v_mul_f32_e32 v190, v190, v170
	v_mul_f32_e32 v154, v150, v190
	v_mul_f32_e32 v191, v191, v171
	v_mul_f32_e32 v155, v151, v191
	v_cvt_pk_bf16_f32 v176, v152, v1
	ds_write_b16 v129, v176
	v_cvt_pk_bf16_f32 v177, v153, v1
	ds_write_b16 v129, v177 offset:144
	v_cvt_pk_bf16_f32 v178, v154, v1
	ds_write_b16 v129, v178 offset:288
	v_cvt_pk_bf16_f32 v179, v155, v1
	ds_write_b16 v129, v179 offset:432
	v_lshlrev_b32_e32 v184, 16, v250
	v_and_b32_e32 v185, 0xffff0000, v250
	v_lshlrev_b32_e32 v186, 16, v251
	v_and_b32_e32 v187, 0xffff0000, v251
	s_waitcnt lgkmcnt(7)
	v_lshlrev_b32_e32 v172, 16, v172
	v_mul_f32_e32 v188, 0xbfb8aa3b, v172
	v_exp_f32_e32 v188, v188
	s_waitcnt lgkmcnt(6)
	v_lshlrev_b32_e32 v173, 16, v173
	v_mul_f32_e32 v189, 0xbfb8aa3b, v173
	v_exp_f32_e32 v189, v189
	s_waitcnt lgkmcnt(5)
	v_lshlrev_b32_e32 v215, 16, v215
	v_mul_f32_e32 v190, 0xbfb8aa3b, v215
	v_exp_f32_e32 v190, v190
	s_waitcnt lgkmcnt(4)
	v_lshlrev_b32_e32 v102, 16, v102
	v_mul_f32_e32 v191, 0xbfb8aa3b, v102
	v_exp_f32_e32 v191, v191
	v_fma_f32 v58, v192, v216, v58
	v_fmac_f32_e32 v58, v95, v184
	v_fma_f32 v59, v193, v217, v59
	v_fmac_f32_e32 v59, v95, v185
	v_fma_f32 v60, v194, v218, v60
	v_fmac_f32_e32 v60, v95, v186
	v_fma_f32 v61, v195, v219, v61
	v_fmac_f32_e32 v61, v95, v187
	v_add_f32_e32 v188, 1.0, v188
	v_rcp_f32_e32 v188, v188
	v_add_f32_e32 v189, 1.0, v189
	v_rcp_f32_e32 v189, v189
	v_add_f32_e32 v190, 1.0, v190
	v_rcp_f32_e32 v190, v190
	v_add_f32_e32 v191, 1.0, v191
	v_rcp_f32_e32 v191, v191
	v_mul_f32_e32 v188, v188, v172
	v_mul_f32_e32 v62, v58, v188
	v_mul_f32_e32 v189, v189, v173
	v_mul_f32_e32 v63, v59, v189
	v_mul_f32_e32 v190, v190, v215
	v_mul_f32_e32 v64, v60, v190
	v_mul_f32_e32 v191, v191, v102
	v_mul_f32_e32 v65, v61, v191
	v_cvt_pk_bf16_f32 v220, v62, v1
	ds_write_b16 v132, v220
	v_cvt_pk_bf16_f32 v221, v63, v1
	ds_write_b16 v132, v221 offset:144
	v_cvt_pk_bf16_f32 v222, v64, v1
	ds_write_b16 v132, v222 offset:288
	v_cvt_pk_bf16_f32 v223, v65, v1
	ds_write_b16 v132, v223 offset:432
	v_mul_f32_e32 v156, v62, v62
	v_fmac_f32_e32 v156, v152, v152
	v_mul_f32_e32 v157, v63, v63
	v_fmac_f32_e32 v157, v153, v153
	v_mul_f32_e32 v158, v64, v64
	v_fmac_f32_e32 v158, v154, v154
	v_mul_f32_e32 v159, v65, v65
	v_fmac_f32_e32 v159, v155, v155
	v_add_f32_dpp v156, v156, v156 quad_perm:[1,0,3,2] row_mask:0xf bank_mask:0xf bound_ctrl:1
	v_add_f32_dpp v157, v157, v157 quad_perm:[1,0,3,2] row_mask:0xf bank_mask:0xf bound_ctrl:1
	v_add_f32_dpp v158, v158, v158 quad_perm:[1,0,3,2] row_mask:0xf bank_mask:0xf bound_ctrl:1
	v_add_f32_dpp v159, v159, v159 quad_perm:[1,0,3,2] row_mask:0xf bank_mask:0xf bound_ctrl:1
	v_add_f32_dpp v156, v156, v156 quad_perm:[2,3,0,1] row_mask:0xf bank_mask:0xf bound_ctrl:1
	v_add_f32_dpp v157, v157, v157 quad_perm:[2,3,0,1] row_mask:0xf bank_mask:0xf bound_ctrl:1
	v_add_f32_dpp v158, v158, v158 quad_perm:[2,3,0,1] row_mask:0xf bank_mask:0xf bound_ctrl:1
	v_add_f32_dpp v159, v159, v159 quad_perm:[2,3,0,1] row_mask:0xf bank_mask:0xf bound_ctrl:1
	v_add_f32_dpp v156, v156, v156 row_half_mirror row_mask:0xf bank_mask:0xf bound_ctrl:1
	v_add_f32_dpp v157, v157, v157 row_half_mirror row_mask:0xf bank_mask:0xf bound_ctrl:1
	v_add_f32_dpp v158, v158, v158 row_half_mirror row_mask:0xf bank_mask:0xf bound_ctrl:1
	v_add_f32_dpp v159, v159, v159 row_half_mirror row_mask:0xf bank_mask:0xf bound_ctrl:1
	v_mov_b32_dpp v160, v156 row_mirror row_mask:0xf bank_mask:0xf bound_ctrl:1
	v_mov_b32_dpp v161, v157 row_mirror row_mask:0xf bank_mask:0xf bound_ctrl:1
	v_mov_b32_dpp v162, v158 row_mirror row_mask:0xf bank_mask:0xf bound_ctrl:1
	v_mov_b32_dpp v163, v159 row_mirror row_mask:0xf bank_mask:0xf bound_ctrl:1
	s_and_saveexec_b64 s[20:21], s[6:7]
	v_add_f32_e32 v156, v156, v160
	v_add_f32_e32 v157, v157, v161
	v_add_f32_e32 v158, v158, v162
	v_add_f32_e32 v159, v159, v163
	ds_write_b32 v133, v156
	ds_write_b32 v134, v157
	ds_write_b32 v135, v158
	ds_write_b32 v136, v159
	s_or_b64 exec, exec, s[20:21]
	s_waitcnt lgkmcnt(0)
	s_barrier
	s_and_saveexec_b64 s[20:21], s[38:39]
	s_cbranch_execz .LBB0_560
	s_nop 1
	ds_read_b64 v[58:59], v145
	v_add_u32_e32 v60, s15, v116
	s_waitcnt lgkmcnt(0)
	v_add_f32_e32 v58, v58, v59
	ds_write_b32 v60, v58
	s_branch .LBB0_560

; __device__ __forceinline__ void norm_mod_rows(const float* __restrict__ xp, const float* __restrict__ xs, const float* __restrict__ gvec, const float* __restrict__ mod, int ch_shift, int ch_scale, ...
;     for (int r0 = gw; r0 < nrows; r0 += 2 * NGW) {
;         const int r1 = r0 + NGW; const bool two = r1 < nrows;
;         const int gr0 = row_base + r0, gr1 = row_base + (two ? r1 : r0);
;         const float* xrow0 = gr0 < MP ? xp + (size_t)gr0 * DM : xs + (size_t)(gr0 - MP) * DM;
;         const float* xrow1 = gr1 < MP ? xp + (size_t)gr1 * DM : xs + (size_t)(gr1 - MP) * DM;
;         f32x4 v0[4], v1[4]; float s0 = 0.f, s1 = 0.f;
; #pragma unroll
;         for (int j = 0; j < 4; ++j) { v0[j] = ((const f32x4*)xrow0)[lane + 64 * j]; v1[j] = ((const f32x4*)xrow1)[lane + 64 * j]; }
; #pragma unroll
;         for (int j = 0; j < 4; ++j) { s0 += (v0[j][0] * v0[j][0] + v0[j][1] * v0[j][1]) + (v0[j][2] * v0[j][2] + v0[j][3] * v0[j][3]);
;                                       s1 += (v1[j][0] * v1[j][0] + v1[j][1] * v1[j][1]) + (v1[j][2] * v1[j][2] + v1[j][3] * v1[j][3]); }
;         const float rstd0 = rsqrtf(wave_sum(s0) * (1.f / DM) + EPS), rstd1 = rsqrtf(wave_sum(s1) * (1.f / DM) + EPS);
; #pragma unroll
;         for (int q = 0; q < 2; ++q) {
;             if (q == 1 && !two) break;
;             const int gr = q ? gr1 : gr0, r = q ? r1 : r0; const float rstd = q ? rstd1 : rstd0;
;             const int seq = gr < MP ? (gr >> 11) : NPB + ((gr - MP) >> 6);
;             const float* mrow = mod + (size_t)seq * (6 * DM);
;             u32x2* o8 = (u32x2*)(H + (size_t)r * DM);
;             f32x4 gq[4], scq[4], shq[4];
; #pragma unroll
;             for (int j = 0; j < 4; ++j) { const int ci = lane + 64 * j;
;                 gq[j] = ((const f32x4*)gvec)[ci]; scq[j] = ((const f32x4*)(mrow + ch_scale * DM))[ci]; shq[j] = ((const f32x4*)(mrow + ch_shift * DM))[ci]; }
.Lnorm_loop_p7:
	s_lshl_b32 s9, s3, 1
	s_add_i32 s10, s9, s8
	s_lshl_b32 s22, s9, 11
	s_add_u32 s20, s12, s22
	s_addc_u32 s21, s13, 0
	s_add_i32 s9, s10, 0xffff8000
	s_ashr_i32 s22, s10, 11
	s_lshr_b32 s16, s9, 6
	s_add_i32 s16, s16, 16
	s_cmp_lt_i32 s10, 0x8000
	s_cselect_b32 s14, s24, s34
	s_cselect_b32 s15, s25, s35
	s_cselect_b32 s9, s10, s9
	s_cselect_b32 s22, s22, s16
	s_lshl_b32 s9, s9, 12
	s_add_u32 s14, s14, s9
	s_addc_u32 s15, s15, 0
	s_mul_i32 s22, s22, 0x6000
	v_readlane_b32 s16, v255, 24
	v_readlane_b32 s17, v255, 26
	s_add_u32 s16, s16, s22
	s_addc_u32 s17, s17, 0
	global_load_dwordx4 v[18:21], v85, s[14:15]
	global_load_dwordx4 v[22:25], v85, s[14:15] offset:1024
	global_load_dwordx4 v[26:29], v85, s[14:15] offset:2048
	global_load_dwordx4 v[30:33], v85, s[14:15] offset:3072
	global_load_dwordx4 v[34:37], v86, s[14:15]
	global_load_dwordx4 v[38:41], v86, s[14:15] offset:1024
	global_load_dwordx4 v[42:45], v86, s[14:15] offset:2048
	global_load_dwordx4 v[46:49], v86, s[14:15] offset:3072
	global_load_dwordx4 v[50:53], v88, s[16:17]
	global_load_dwordx4 v[54:57], v88, s[16:17] offset:1024
	global_load_dwordx4 v[58:61], v88, s[16:17] offset:2048
	global_load_dwordx4 v[62:65], v88, s[16:17] offset:3072
	global_load_dwordx4 v[66:69], v87, s[16:17]
	global_load_dwordx4 v[70:73], v87, s[16:17] offset:1024
	global_load_dwordx4 v[74:77], v87, s[16:17] offset:2048
	global_load_dwordx4 v[78:81], v87, s[16:17] offset:3072
	s_waitcnt vmcnt(15)
	v_pk_mul_f32 v[82:83], v[18:19], v[18:19]
	v_pk_fma_f32 v[82:83], v[20:21], v[20:21], v[82:83]
	s_waitcnt vmcnt(14)
	v_pk_fma_f32 v[82:83], v[22:23], v[22:23], v[82:83]
	v_pk_fma_f32 v[82:83], v[24:25], v[24:25], v[82:83]
	s_waitcnt vmcnt(13)
	v_pk_fma_f32 v[82:83], v[26:27], v[26:27], v[82:83]
	v_pk_fma_f32 v[82:83], v[28:29], v[28:29], v[82:83]
	s_waitcnt vmcnt(12)
	v_pk_fma_f32 v[82:83], v[30:31], v[30:31], v[82:83]
	v_pk_fma_f32 v[82:83], v[32:33], v[32:33], v[82:83]
	s_waitcnt vmcnt(11)
	v_pk_mul_f32 v[90:91], v[34:35], v[34:35]
	v_pk_fma_f32 v[90:91], v[36:37], v[36:37], v[90:91]
	s_waitcnt vmcnt(10)
	v_pk_fma_f32 v[90:91], v[38:39], v[38:39], v[90:91]
	v_pk_fma_f32 v[90:91], v[40:41], v[40:41], v[90:91]
	s_waitcnt vmcnt(9)
	v_pk_fma_f32 v[90:91], v[42:43], v[42:43], v[90:91]
	v_pk_fma_f32 v[90:91], v[44:45], v[44:45], v[90:91]
	s_waitcnt vmcnt(8)
	v_pk_fma_f32 v[90:91], v[46:47], v[46:47], v[90:91]
	v_pk_fma_f32 v[90:91], v[48:49], v[48:49], v[90:91]
	s_nop 0
	v_add_f32_e32 v82, v82, v83
	v_add_f32_e32 v90, v90, v91
	s_nop 1
	v_add_f32_dpp v82, v82, v82 quad_perm:[1,0,3,2] row_mask:0xf bank_mask:0xf bound_ctrl:1
	v_add_f32_dpp v90, v90, v90 quad_perm:[1,0,3,2] row_mask:0xf bank_mask:0xf bound_ctrl:1
	s_nop 1
	v_add_f32_dpp v82, v82, v82 quad_perm:[2,3,0,1] row_mask:0xf bank_mask:0xf bound_ctrl:1
	v_add_f32_dpp v90, v90, v90 quad_perm:[2,3,0,1] row_mask:0xf bank_mask:0xf bound_ctrl:1
	s_nop 1
	v_add_f32_dpp v82, v82, v82 row_half_mirror row_mask:0xf bank_mask:0xf bound_ctrl:1
	v_add_f32_dpp v90, v90, v90 row_half_mirror row_mask:0xf bank_mask:0xf bound_ctrl:1
	s_nop 1
	v_add_f32_dpp v82, v82, v82 row_mirror row_mask:0xf bank_mask:0xf bound_ctrl:1
	v_add_f32_dpp v90, v90, v90 row_mirror row_mask:0xf bank_mask:0xf bound_ctrl:1
	s_nop 1
	v_add_f32_dpp v82, v82, v82 row_bcast:15 row_mask:0xa bank_mask:0xf
	v_add_f32_dpp v90, v90, v90 row_bcast:15 row_mask:0xa bank_mask:0xf
	s_nop 1
	v_add_f32_dpp v82, v82, v82 row_bcast:31 row_mask:0xc bank_mask:0xf
	v_add_f32_dpp v90, v90, v90 row_bcast:31 row_mask:0xc bank_mask:0xf
	s_nop 1
	v_readlane_b32 s9, v82, 63
	v_readlane_b32 s10, v90, 63
	s_nop 2
	v_mov_b32_e32 v92, s9
	v_mov_b32_e32 v94, s10
	v_fmamk_f32 v92, v92, 0x3a800000, v167
	v_fmamk_f32 v94, v94, 0x3a800000, v167
	v_rsq_f32_e32 v92, v92
	v_rsq_f32_e32 v94, v94
	s_waitcnt vmcnt(4)
; __device__ __forceinline__ unsigned pk2(float lo, float hi) { unsigned r; asm("v_cvt_pk_bf16_f32 %0, %1, %2" : "=v"(r) : "v"(lo), "v"(hi)); return r; }
; __device__ __forceinline__ void norm_mod_rows(const float* __restrict__ xp, const float* __restrict__ xs, const float* __restrict__ gvec, const float* __restrict__ mod, int ch_shift, int ch_scale, ...
;     ...
; #pragma unroll
;             for (int j = 0; j < 4; ++j) { const int ci = lane + 64 * j;
;                 const f32x4 y = ((q ? v1[j] : v0[j]) * rstd) * gq[j] * (scq[j] + 1.f) + shq[j];
;                 u32x2 w; w.x = pk2(y[0], y[1]); w.y = pk2(y[2], y[3]); o8[ci] = w; }
;         }
	v_pk_add_f32 v[50:51], v[50:51], 1.0 op_sel_hi:[1,0]
	v_pk_add_f32 v[52:53], v[52:53], 1.0 op_sel_hi:[1,0]
	v_pk_add_f32 v[54:55], v[54:55], 1.0 op_sel_hi:[1,0]
	v_pk_add_f32 v[56:57], v[56:57], 1.0 op_sel_hi:[1,0]
	v_pk_add_f32 v[58:59], v[58:59], 1.0 op_sel_hi:[1,0]
	v_pk_add_f32 v[60:61], v[60:61], 1.0 op_sel_hi:[1,0]
	v_pk_add_f32 v[62:63], v[62:63], 1.0 op_sel_hi:[1,0]
	v_pk_add_f32 v[64:65], v[64:65], 1.0 op_sel_hi:[1,0]
	s_waitcnt vmcnt(0)
	v_pk_mul_f32 v[18:19], v[18:19], v[92:93] op_sel_hi:[1,0]
	v_pk_mul_f32 v[20:21], v[20:21], v[92:93] op_sel_hi:[1,0]
	v_pk_mul_f32 v[22:23], v[22:23], v[92:93] op_sel_hi:[1,0]
	v_pk_mul_f32 v[24:25], v[24:25], v[92:93] op_sel_hi:[1,0]
	v_pk_mul_f32 v[26:27], v[26:27], v[92:93] op_sel_hi:[1,0]
	v_pk_mul_f32 v[28:29], v[28:29], v[92:93] op_sel_hi:[1,0]
	v_pk_mul_f32 v[30:31], v[30:31], v[92:93] op_sel_hi:[1,0]
	v_pk_mul_f32 v[32:33], v[32:33], v[92:93] op_sel_hi:[1,0]
	v_pk_mul_f32 v[18:19], v[2:3], v[18:19]
	v_pk_mul_f32 v[20:21], v[4:5], v[20:21]
	v_pk_mul_f32 v[22:23], v[6:7], v[22:23]
	v_pk_mul_f32 v[24:25], v[8:9], v[24:25]
	v_pk_mul_f32 v[26:27], v[10:11], v[26:27]
	v_pk_mul_f32 v[28:29], v[12:13], v[28:29]
	v_pk_mul_f32 v[30:31], v[14:15], v[30:31]
	v_pk_mul_f32 v[32:33], v[16:17], v[32:33]
	v_pk_fma_f32 v[18:19], v[50:51], v[18:19], v[66:67]
	v_pk_fma_f32 v[20:21], v[52:53], v[20:21], v[68:69]
	v_pk_fma_f32 v[22:23], v[54:55], v[22:23], v[70:71]
	v_pk_fma_f32 v[24:25], v[56:57], v[24:25], v[72:73]
	v_pk_fma_f32 v[26:27], v[58:59], v[26:27], v[74:75]
	v_pk_fma_f32 v[28:29], v[60:61], v[28:29], v[76:77]
	v_pk_fma_f32 v[30:31], v[62:63], v[30:31], v[78:79]
	v_pk_fma_f32 v[32:33], v[64:65], v[32:33], v[80:81]
	v_cvt_pk_bf16_f32 v18, v18, v19
	v_cvt_pk_bf16_f32 v19, v20, v21
	v_cvt_pk_bf16_f32 v22, v22, v23
	v_cvt_pk_bf16_f32 v23, v24, v25
	v_cvt_pk_bf16_f32 v26, v26, v27
	v_cvt_pk_bf16_f32 v27, v28, v29
	v_cvt_pk_bf16_f32 v30, v30, v31
	v_cvt_pk_bf16_f32 v31, v32, v33
	global_store_dwordx2 v0, v[18:19], s[20:21]
	global_store_dwordx2 v0, v[22:23], s[20:21] offset:512
	global_store_dwordx2 v0, v[26:27], s[20:21] offset:1024
	global_store_dwordx2 v0, v[30:31], s[20:21] offset:1536
	v_pk_mul_f32 v[34:35], v[34:35], v[94:95] op_sel_hi:[1,0]
	v_pk_mul_f32 v[36:37], v[36:37], v[94:95] op_sel_hi:[1,0]
	v_pk_mul_f32 v[38:39], v[38:39], v[94:95] op_sel_hi:[1,0]
	v_pk_mul_f32 v[40:41], v[40:41], v[94:95] op_sel_hi:[1,0]
	v_pk_mul_f32 v[42:43], v[42:43], v[94:95] op_sel_hi:[1,0]
	v_pk_mul_f32 v[44:45], v[44:45], v[94:95] op_sel_hi:[1,0]
	v_pk_mul_f32 v[46:47], v[46:47], v[94:95] op_sel_hi:[1,0]
	v_pk_mul_f32 v[48:49], v[48:49], v[94:95] op_sel_hi:[1,0]
	v_pk_mul_f32 v[34:35], v[2:3], v[34:35]
	v_pk_mul_f32 v[36:37], v[4:5], v[36:37]
	v_pk_mul_f32 v[38:39], v[6:7], v[38:39]
	v_pk_mul_f32 v[40:41], v[8:9], v[40:41]
	v_pk_mul_f32 v[42:43], v[10:11], v[42:43]
	v_pk_mul_f32 v[44:45], v[12:13], v[44:45]
	v_pk_mul_f32 v[46:47], v[14:15], v[46:47]
	v_pk_mul_f32 v[48:49], v[16:17], v[48:49]
	v_pk_fma_f32 v[34:35], v[50:51], v[34:35], v[66:67]
	v_pk_fma_f32 v[36:37], v[52:53], v[36:37], v[68:69]
	v_pk_fma_f32 v[38:39], v[54:55], v[38:39], v[70:71]
	v_pk_fma_f32 v[40:41], v[56:57], v[40:41], v[72:73]
	v_pk_fma_f32 v[42:43], v[58:59], v[42:43], v[74:75]
	v_pk_fma_f32 v[44:45], v[60:61], v[44:45], v[76:77]
	v_pk_fma_f32 v[46:47], v[62:63], v[46:47], v[78:79]
	v_pk_fma_f32 v[48:49], v[64:65], v[48:49], v[80:81]
	v_cvt_pk_bf16_f32 v34, v34, v35
	v_cvt_pk_bf16_f32 v35, v36, v37
	v_cvt_pk_bf16_f32 v38, v38, v39
	v_cvt_pk_bf16_f32 v39, v40, v41
	v_cvt_pk_bf16_f32 v42, v42, v43
	v_cvt_pk_bf16_f32 v43, v44, v45
	v_cvt_pk_bf16_f32 v46, v46, v47
	v_cvt_pk_bf16_f32 v47, v48, v49
	global_store_dwordx2 v0, v[34:35], s[20:21] offset:2048
	global_store_dwordx2 v0, v[38:39], s[20:21] offset:2560
	global_store_dwordx2 v0, v[42:43], s[20:21] offset:3072
	global_store_dwordx2 v0, v[46:47], s[20:21] offset:3584
	s_add_i32 s3, s3, s5
	s_cmp_lt_i32 s3, s4
	s_cbranch_scc1 .Lnorm_loop_p7
